# P4 chain loop: LDS buffer-parity arithmetic folded per body, silu in packed f32 ops, dead compare and copies removed
# speedup vs baseline: 1.0047x; 1.0041x over previous
.Lp4n_tab:
	v_mbcnt_lo_u32_b32 v229, -1, 0
	v_mbcnt_hi_u32_b32 v229, -1, v229
	v_and_b32_e32 v230, s61, v229
	v_lshrrev_b32_e32 v231, s62, v229
	v_lshrrev_b32_e32 v232, 1, v231
	v_add_u32_e32 v232, s59, v232
	v_and_b32_e32 v232, 7, v232
	v_add_u32_e32 v233, s60, v231
	v_and_b32_e32 v233, 1, v233
	v_sub_u32_e32 v234, s61, v230
	v_cmp_eq_u32_e32 vcc, 1, v233
	s_nop 1
	v_cndmask_b32_e32 v235, v230, v234, vcc
	v_add_u32_e32 v235, s64, v235
	v_cmp_eq_u32_e32 vcc, s61, v230
	s_nop 1
	v_cndmask_b32_e64 v236, 0, 1, vcc
	v_lshlrev_b32_e32 v237, 9, v232
	v_or_b32_e32 v220, v235, v237
	v_lshlrev_b32_e32 v237, 12, v233
	v_or_b32_e32 v220, v220, v237
	s_lshl_b32 s45, s57, 13
	s_lshl_b32 s46, s58, 15
	s_or_b32 s45, s45, s46
	s_lshl_b32 s46, s63, 20
	s_or_b32 s45, s45, s46
	v_or_b32_e32 v220, s45, v220
	v_lshlrev_b32_e32 v237, 21, v236
	v_or_b32_e32 v220, v220, v237
	v_lshlrev_b32_e32 v237, 22, v230
	v_or_b32_e32 v220, v220, v237
	v_lshl_add_u32 v237, v235, 3, v232
	v_lshlrev_b32_e32 v221, 14, v237
	v_lshlrev_b32_e32 v238, 8, v233
	v_lshl_add_u32 v224, v237, 10, v238
	v_lshlrev_b32_e32 v238, 8, v232
	v_lshl_add_u32 v222, v235, 17, v238
	s_mov_b32 s45, 0xc0000
	v_mul_lo_u32 v237, v235, s45
	s_lshl_b32 s46, s57, 6
	s_sub_u32 s46, s46, 0x5000
	v_add_u32_e32 v238, s46, v238
	v_add_u32_e32 v223, v237, v238
	s_mov_b32 s45, 0x60000
	v_mul_lo_u32 v237, v235, s45
	v_lshlrev_b32_e32 v238, 10, v233
	v_lshl_add_u32 v238, v232, 7, v238
	s_lshl_b32 s46, s57, 5
	v_add_u32_e32 v238, s46, v238
	v_add_u32_e32 v227, v237, v238
	v_lshlrev_b32_e32 v228, 6, v235
	v_mov_b32_e32 v225, s65
	v_mov_b32_e32 v226, s66
	s_mov_b32 s99, 0
	s_mov_b32 s100, 0xbfb8aa3b
	s_mov_b32 s101, 0xbfb8aa3b
	s_nop 1
	v_readlane_b32 s41, v220, 0
	v_readlane_b32 s42, v220, 1
	v_readlane_b32 s43, v220, 2
.Lp4n_top_A:
	s_cmp_lt_u32 s99, 63
	s_cselect_b64 s[10:11], -1, 0
	ds_read_b128 v[102:105], v193 offset:31232
	ds_read_b128 v[106:109], v192 offset:48640
	ds_read_b128 v[110:113], v192 offset:48704
	ds_read_b128 v[114:117], v193 offset:31296
	ds_read_b128 v[198:201], v190
	ds_read_b128 v[202:205], v190 offset:64
	s_waitcnt lgkmcnt(0)
	v_mfma_f32_16x16x32_bf16 v[102:105], v[102:105], v[106:109], 0
	s_mov_b32 s87, 0x1d400
	s_waitcnt lgkmcnt(1)
	v_mfma_f32_16x16x32_bf16 v[106:109], v[198:201], v[106:109], 0
	v_mfma_f32_16x16x32_bf16 v[102:105], v[114:117], v[110:113], v[102:105]
	ds_read_b128 v[114:117], v193 offset:31360
	ds_read_b128 v[198:201], v192 offset:48768
	s_waitcnt lgkmcnt(2)
	v_mfma_f32_16x16x32_bf16 v[106:109], v[202:205], v[110:113], v[106:109]
	ds_read_b128 v[110:113], v193 offset:31424
	ds_read_b128 v[202:205], v192 offset:48832
	s_waitcnt lgkmcnt(2)
	v_mfma_f32_16x16x32_bf16 v[102:105], v[114:117], v[198:201], v[102:105]
	ds_read_b128 v[114:117], v190 offset:128
	ds_read_b128 v[206:209], v190 offset:192
	v_lshl_add_u32 v159, v189, 2, s87
	s_waitcnt lgkmcnt(2)
	v_mfma_f32_16x16x32_bf16 v[102:105], v[110:113], v[202:205], v[102:105]
	ds_read_b128 v[110:113], v159 offset:512
	s_waitcnt lgkmcnt(2)
	v_mfma_f32_16x16x32_bf16 v[106:109], v[114:117], v[198:201], v[106:109]
	s_nop 4
	v_sub_f32_e32 v105, v101, v105
	v_sub_f32_e32 v104, v100, v104
	v_sub_f32_e32 v103, v99, v103
	v_sub_f32_e32 v102, v98, v102
	v_cvt_pk_bf16_f32 v114, v102, v103
	s_waitcnt lgkmcnt(0)
	v_pk_mul_f32 v[102:103], v[102:103], v[110:111]
	v_cvt_pk_bf16_f32 v115, v104, v105
	v_pk_mul_f32 v[104:105], v[104:105], v[112:113]
	v_cvt_pk_bf16_f32 v102, v102, v103
	v_cvt_pk_bf16_f32 v103, v104, v105
	ds_write2st64_b64 v194, v[114:115], v[102:103] offset0:112 offset1:121
	ds_read_b128 v[110:113], v159
	v_mfma_f32_16x16x32_bf16 v[114:117], v[206:209], v[202:205], v[106:109]
.Lp4n_stg_A:
	s_cmp_lt_u32 s99, 63
	s_cbranch_scc0 .Lp4n_premid_A
	s_bfe_u32 s45, s42, 0x1000c
	s_cmp_eq_u32 s45, 0
	s_cselect_b64 vcc, -1, 0
	v_add_u32_e32 v102, 0x4400, v169
	v_cndmask_b32_e32 v106, v162, v161, vcc
	v_cndmask_b32_e32 v107, v164, v163, vcc
	v_cndmask_b32_e32 v108, v166, v165, vcc
	v_cndmask_b32_e32 v109, v168, v167, vcc
	s_waitcnt vmcnt(11)
	ds_write_b128 v102, v[34:37]
	s_waitcnt vmcnt(10)
	ds_write_b128 v102, v[38:41] offset:8704
	ds_write_b128 v170, v[26:29]
	ds_write_b128 v170, v[30:33] offset:9216
	s_waitcnt vmcnt(9)
	v_and_b32_e32 v102, v42, v106
	v_and_b32_e32 v103, v43, v107
	v_and_b32_e32 v104, v44, v108
	v_and_b32_e32 v105, v45, v109
	ds_write_b128 v171, v[102:105] offset:17408
	s_waitcnt vmcnt(8)
	v_and_b32_e32 v102, v46, v106
	v_and_b32_e32 v103, v47, v107
	v_and_b32_e32 v104, v48, v108
	v_and_b32_e32 v105, v49, v109
	v_add_u32_e32 v106, 0x2400, v172
	s_bfe_u32 s45, s42, 0x60016
	s_cmp_lg_u32 s45, 0
	ds_write_b128 v106, v[102:105]
	s_cbranch_scc1 .Lp4n_cwkeep_A
	s_waitcnt vmcnt(4)
	v_mov_b64_e32 v[84:85], v[24:25]
	v_mov_b64_e32 v[88:89], v[20:21]
	v_mov_b64_e32 v[92:93], v[16:17]
	v_mov_b64_e32 v[96:97], v[12:13]
	v_mov_b64_e32 v[82:83], v[22:23]
	v_mov_b64_e32 v[86:87], v[18:19]
	v_mov_b64_e32 v[90:91], v[14:15]
	v_mov_b64_e32 v[94:95], v[10:11]
.Lp4n_cwkeep_A:
	v_lshlrev_b32_e32 v102, 16, v128
	v_and_b32_e32 v103, 0xffff0000, v128
	v_pk_mul_f32 v[102:103], v[94:95], v[102:103]
	v_lshlrev_b32_e32 v104, 16, v129
	v_and_b32_e32 v105, 0xffff0000, v129
	v_pk_mul_f32 v[104:105], v[96:97], v[104:105]
	v_lshlrev_b32_e32 v106, 16, v130
	v_and_b32_e32 v107, 0xffff0000, v130
	v_pk_fma_f32 v[102:103], v[90:91], v[106:107], v[102:103]
	v_lshlrev_b32_e32 v108, 16, v131
	v_and_b32_e32 v109, 0xffff0000, v131
	v_pk_fma_f32 v[104:105], v[92:93], v[108:109], v[104:105]
	v_lshlrev_b32_e32 v106, 16, v132
	v_and_b32_e32 v107, 0xffff0000, v132
	v_pk_fma_f32 v[102:103], v[86:87], v[106:107], v[102:103]
	v_lshlrev_b32_e32 v108, 16, v133
	v_and_b32_e32 v109, 0xffff0000, v133
	v_pk_fma_f32 v[104:105], v[88:89], v[108:109], v[104:105]
	v_lshlrev_b32_e32 v106, 16, v136
	v_and_b32_e32 v107, 0xffff0000, v136
	v_pk_fma_f32 v[102:103], v[82:83], v[106:107], v[102:103]
	v_lshlrev_b32_e32 v108, 16, v137
	v_and_b32_e32 v109, 0xffff0000, v137
	v_pk_fma_f32 v[104:105], v[84:85], v[108:109], v[104:105]
	v_pk_mul_f32 v[106:107], v[102:103], s[100:101] op_sel_hi:[1,0]
	v_pk_mul_f32 v[108:109], v[104:105], s[100:101] op_sel_hi:[1,0]
	v_exp_f32_e32 v106, v106
	v_exp_f32_e32 v107, v107
	v_exp_f32_e32 v108, v108
	v_exp_f32_e32 v109, v109
	v_pk_add_f32 v[106:107], v[106:107], 1.0 op_sel_hi:[1,0]
	v_pk_add_f32 v[108:109], v[108:109], 1.0 op_sel_hi:[1,0]
	v_rcp_f32_e32 v106, v106
	v_rcp_f32_e32 v107, v107
	v_rcp_f32_e32 v108, v108
	v_rcp_f32_e32 v109, v109
	v_pk_mul_f32 v[102:103], v[102:103], v[106:107]
	v_pk_mul_f32 v[104:105], v[104:105], v[108:109]
	s_waitcnt vmcnt(7)
	v_mul_f32_e32 v102, v175, v102
	v_mul_f32_e32 v103, v175, v103
	v_mul_f32_e32 v104, v175, v104
	v_mul_f32_e32 v105, v175, v105
	v_cvt_pk_bf16_f32 v102, v102, s0
	v_cvt_pk_bf16_f32 v103, v103, s0
	v_cvt_pk_bf16_f32 v104, v104, s0
	v_cvt_pk_bf16_f32 v105, v105, s0
	v_add_u32_e32 v106, v173, v182
	ds_write_b16 v106, v102 offset:26624
	ds_write_b16 v106, v103 offset:26768
	ds_write_b16 v106, v104 offset:26912
	ds_write_b16 v106, v105 offset:27056
	s_and_saveexec_b64 s[8:9], s[4:5]
	s_cbranch_execz .Lp4n_w0done_A
	s_mov_b32 s14, 0x1d900
	s_and_b64 s[20:21], vcc, exec
	s_cselect_b32 s20, 63, 0
	v_and_or_b32 v102, v195, 64, s20
	v_lshlrev_b32_e32 v102, 2, v102
	ds_bpermute_b32 v102, v102, v176
	v_mul_f32_e32 v103, 0x3fb8aa3b, v176
	v_exp_f32_e32 v103, v103
	v_lshl_add_u32 v105, v0, 2, s14
	s_waitcnt lgkmcnt(0)
	v_sub_f32_e32 v104, v102, v176
	v_mul_f32_e32 v104, 0x3fb8aa3b, v104
	v_exp_f32_e32 v104, v104
	v_mul_f32_e32 v106, v177, v103
	ds_write2st64_b32 v105, v103, v106 offset1:1
	ds_write_b32 v105, v104 offset:512
	s_and_b64 exec, exec, s[6:7]
	s_cbranch_execz .Lp4n_w0done_A
	v_mul_f32_e32 v102, 0x3fb8aa3b, v102
	v_exp_f32_e32 v102, v102
	v_mov_b32_e32 v103, s14
	ds_write_b32 v103, v102 offset:768

.Lp4n_premid_A:
.Lp4n_mid_A:
	s_waitcnt lgkmcnt(0)
	s_barrier
	v_mov_b32_e32 v102, s87
	ds_read_b32 v198, v102 offset:768
	ds_read_b128 v[102:105], v196 offset:61952
	ds_read_b128 v[106:109], v196 offset:64256
	s_waitcnt lgkmcnt(2)
	v_pk_mul_f32 v[4:5], v[4:5], v[198:199] op_sel_hi:[1,0]
	v_pk_mul_f32 v[2:3], v[2:3], v[198:199] op_sel_hi:[1,0]
	v_pk_mul_f32 v[8:9], v[8:9], v[198:199] op_sel_hi:[1,0]
	v_pk_mul_f32 v[6:7], v[6:7], v[198:199] op_sel_hi:[1,0]
	s_waitcnt lgkmcnt(1)
	v_mfma_f32_16x16x32_bf16 v[2:5], v[74:77], v[102:105], v[2:5]
	ds_read_b128 v[102:105], v196 offset:62016
	s_waitcnt lgkmcnt(1)
	v_mfma_f32_16x16x32_bf16 v[6:9], v[74:77], v[106:109], v[6:9]
	v_readlane_b32 s8, v227, s99
	s_mov_b32 s9, 0
	s_waitcnt lgkmcnt(0)
	v_mfma_f32_16x16x32_bf16 v[102:105], v[78:81], v[102:105], v[2:5]
	s_nop 2
	ds_read_b128 v[2:5], v196 offset:64320
	ds_read_b128 v[198:201], v191
	ds_read_b128 v[202:205], v187 offset:57344
	s_waitcnt lgkmcnt(2)
	v_mfma_f32_16x16x32_bf16 v[106:109], v[78:81], v[2:5], v[6:9]
	v_mul_f32_e64 v4, v116, v112
	v_mul_f32_e64 v5, v117, v113
	v_pk_mul_f32 v[2:3], v[114:115], v[110:111]
	ds_read_b128 v[110:113], v191 offset:64
	ds_read_b128 v[6:9], v187 offset:57408
	s_waitcnt lgkmcnt(2)
	v_mfma_f32_16x16x32_bf16 v[2:5], v[198:201], v[202:205], v[2:5]
	s_bfe_u32 s45, s41, 0x10015
	s_cmp_eq_u32 s45, 0
	s_waitcnt lgkmcnt(0)
	v_mfma_f32_16x16x32_bf16 v[2:5], v[110:113], v[6:9], v[2:5]
	v_lshl_add_u64 v[6:7], s[8:9], 1, v[156:157]
	s_movk_i32 s8, 0x6000
	s_nop 5
	v_cvt_pk_bf16_f32 v2, v2, s0
	global_store_short v[6:7], v2, off
	v_add_co_u32_e32 v2, vcc, s50, v6
	v_cvt_pk_bf16_f32 v8, v3, s0
	s_nop 0
	v_addc_co_u32_e32 v3, vcc, 0, v7, vcc
	global_store_short v[2:3], v8, off
	v_add_co_u32_e32 v2, vcc, s8, v6
	v_cvt_pk_bf16_f32 v4, v4, s0
	s_nop 0
	v_addc_co_u32_e32 v3, vcc, 0, v7, vcc
	global_store_short v[2:3], v4, off
	v_add_co_u32_e32 v2, vcc, 0x9000, v6
	v_cvt_pk_bf16_f32 v4, v5, s0
	s_nop 0
	v_addc_co_u32_e32 v3, vcc, 0, v7, vcc
	global_store_short v[2:3], v4, off
	s_cbranch_scc1 .Lp4n_sjoin_A
	s_bfe_u32 s45, s41, 0x10014
	s_cmp_lg_u32 s45, 0
	s_cbranch_scc1 .Lp4n_nosst_A
	s_bfe_u32 s8, s41, 0x5000f
	s_lshl_b32 s8, s8, 4
	s_bfe_u32 s9, s41, 0x1000c
	s_lshl_b32 s9, s9, 3
	s_bfe_u32 s14, s41, 0x30009
	s_add_i32 s8, s14, s8
	s_bfe_u32 s14, s41, 0x2000d
	s_lshl_b32 s14, s14, 5
	s_add_i32 s8, s8, s9
	s_ashr_i32 s9, s8, 31
	s_lshl_b64 s[8:9], s[8:9], 16
	s_add_u32 s20, s72, s8
	s_addc_u32 s21, s73, s9
	s_lshl_b64 s[8:9], s[14:15], 2
	s_add_u32 s8, s20, s8
	s_addc_u32 s9, s21, s9
	v_lshl_add_u64 v[2:3], s[8:9], 0, v[126:127]
	v_lshl_add_u64 v[2:3], v[2:3], 0, s[18:19]
	v_lshl_add_u64 v[4:5], v[2:3], 0, v[144:145]
	v_lshl_add_u64 v[6:7], v[2:3], 0, v[146:147]
	v_lshl_add_u64 v[8:9], v[2:3], 0, v[148:149]
	v_lshl_add_u64 v[2:3], v[2:3], 0, v[150:151]
	global_store_dword v[4:5], v102, off
	global_store_dword v[6:7], v103, off
	global_store_dword v[8:9], v104, off
	global_store_dword v[2:3], v105, off
	global_store_dword v[4:5], v106, off offset:64
	global_store_dword v[6:7], v107, off offset:64
	global_store_dword v[8:9], v108, off offset:64
	global_store_dword v[2:3], v109, off offset:64

.Lp4n_sjoin_A:
	s_nop 0
	v_cvt_pk_bf16_f32 v2, v102, v103
	v_cvt_pk_bf16_f32 v3, v104, v105
	ds_write_b64 v183, v[2:3] offset:48640
	v_cvt_pk_bf16_f32 v2, v106, v107
	v_cvt_pk_bf16_f32 v3, v108, v109
	s_andn2_b64 vcc, exec, s[10:11]
	ds_write_b64 v183, v[2:3] offset:52992
	s_cbranch_vccnz .Lp4n_end_A
	ds_read_b128 v[74:77], v179
	v_add_u32_e32 v159, 0x1da00, v180
	ds_read_b128 v[2:5], v159
	ds_read_b128 v[6:9], v159 offset:16
	ds_read_b128 v[78:81], v179 offset:64
	s_waitcnt lgkmcnt(3)
	v_lshlrev_b32_e32 v98, 16, v74
	v_and_b32_e32 v99, 0xffff0000, v74
	s_waitcnt lgkmcnt(2)
	v_pk_mul_f32 v[2:3], v[2:3], v[98:99]
	v_lshlrev_b32_e32 v98, 16, v75
	v_and_b32_e32 v99, 0xffff0000, v75
	v_pk_mul_f32 v[4:5], v[4:5], v[98:99]
	v_cvt_pk_bf16_f32 v2, v2, v3
	v_cvt_pk_bf16_f32 v3, v4, v5
	v_lshlrev_b32_e32 v4, 16, v76
	v_and_b32_e32 v5, 0xffff0000, v76
	s_waitcnt lgkmcnt(1)
	v_pk_mul_f32 v[4:5], v[6:7], v[4:5]
	v_lshlrev_b32_e32 v6, 16, v77
	v_and_b32_e32 v7, 0xffff0000, v77
	v_pk_mul_f32 v[6:7], v[8:9], v[6:7]
	v_cvt_pk_bf16_f32 v4, v4, v5
	v_cvt_pk_bf16_f32 v5, v6, v7
	ds_read_b128 v[6:9], v196 offset:17408
	ds_read_b128 v[98:101], v196 offset:17472
	ds_read_b128 v[110:113], v196 offset:19712
	ds_read_b128 v[114:117], v196 offset:19776
	ds_read_b128 v[198:201], v196 offset:22016
	ds_read_b128 v[202:205], v196 offset:22080
	ds_read_b128 v[206:209], v196 offset:24320
	ds_read_b128 v[210:213], v159 offset:128
	ds_read_b128 v[214:217], v196 offset:24384
	s_waitcnt lgkmcnt(8)
	v_mfma_f32_16x16x32_bf16 v[6:9], v[2:5], v[6:9], 0
	v_lshlrev_b32_e32 v218, 16, v78
	v_and_b32_e32 v219, 0xffff0000, v78
	s_waitcnt lgkmcnt(1)
	v_pk_mul_f32 v[210:211], v[210:211], v[218:219]
	v_mfma_f32_16x16x32_bf16 v[110:113], v[2:5], v[110:113], 0
	v_lshlrev_b32_e32 v218, 16, v79
	v_and_b32_e32 v219, 0xffff0000, v79
	v_pk_mul_f32 v[212:213], v[212:213], v[218:219]
	v_mfma_f32_16x16x32_bf16 v[198:201], v[2:5], v[198:201], 0
	v_cvt_pk_bf16_f32 v210, v210, v211
	v_cvt_pk_bf16_f32 v211, v212, v213
	v_lshlrev_b32_e32 v212, 16, v80
	v_mfma_f32_16x16x32_bf16 v[2:5], v[2:5], v[206:209], 0
	ds_read_b128 v[206:209], v159 offset:144
	v_and_b32_e32 v213, 0xffff0000, v80
	s_waitcnt lgkmcnt(0)
	v_pk_mul_f32 v[206:207], v[206:207], v[212:213]
	s_nop 0
	v_cvt_pk_bf16_f32 v212, v206, v207
	v_lshlrev_b32_e32 v206, 16, v81
	v_and_b32_e32 v207, 0xffff0000, v81
	v_pk_mul_f32 v[206:207], v[208:209], v[206:207]
	s_nop 0
	v_cvt_pk_bf16_f32 v213, v206, v207
	s_nop 1
	v_mfma_f32_16x16x32_bf16 v[6:9], v[210:213], v[98:101], v[6:9]
	v_mfma_f32_16x16x32_bf16 v[98:101], v[210:213], v[114:117], v[110:113]
	s_nop 6
	v_cvt_pk_bf16_f32 v6, v6, v7
	v_cvt_pk_bf16_f32 v7, v8, v9
	ds_write_b64 v183, v[6:7] offset:31232
	v_mfma_f32_16x16x32_bf16 v[110:113], v[210:213], v[202:205], v[198:201]
	v_add_u32_e32 v8, v174, v188
	v_cvt_pk_bf16_f32 v6, v98, v99
	v_cvt_pk_bf16_f32 v7, v100, v101
	v_mfma_f32_16x16x32_bf16 v[2:5], v[210:213], v[214:217], v[2:5]
	ds_write_b64 v183, v[6:7] offset:35584
	s_nop 2
	v_cvt_pk_bf16_f32 v6, v110, v111
	v_cvt_pk_bf16_f32 v7, v112, v113
	ds_write_b64 v8, v[6:7] offset:31232
	s_nop 0
	v_cvt_pk_bf16_f32 v2, v2, v3
	v_cvt_pk_bf16_f32 v3, v4, v5
	ds_write_b64 v8, v[2:3] offset:35584
	ds_read_b128 v[2:5], v186 offset:17408
	ds_read_b128 v[6:9], v186 offset:17472
	ds_read_b128 v[98:101], v187 offset:26624
	ds_read_b128 v[110:113], v187 offset:26688
	s_waitcnt lgkmcnt(1)
	v_mfma_f32_16x16x32_bf16 v[2:5], v[2:5], v[98:101], 0
	s_waitcnt lgkmcnt(0)
	v_mfma_f32_16x16x32_bf16 v[98:101], v[6:9], v[110:113], v[2:5]

.Lp4n_top_B:
	s_cmp_lt_u32 s99, 63
	s_cselect_b64 s[10:11], -1, 0
	ds_read_b128 v[2:5], v193 offset:31232
	ds_read_b128 v[6:9], v192 offset:48640
	v_add_u32_e32 v159, 0x4400, v190
	ds_read_b128 v[110:113], v192 offset:48704
	ds_read_b128 v[114:117], v193 offset:31296
	ds_read_b128 v[198:201], v159
	ds_read_b128 v[202:205], v159 offset:64
	s_waitcnt lgkmcnt(0)
	v_mfma_f32_16x16x32_bf16 v[2:5], v[2:5], v[6:9], 0
	s_mov_b32 s87, 0x1d900
	s_waitcnt lgkmcnt(1)
	v_mfma_f32_16x16x32_bf16 v[6:9], v[198:201], v[6:9], 0
	v_mfma_f32_16x16x32_bf16 v[2:5], v[114:117], v[110:113], v[2:5]
	ds_read_b128 v[114:117], v193 offset:31360
	ds_read_b128 v[198:201], v192 offset:48768
	s_waitcnt lgkmcnt(2)
	v_mfma_f32_16x16x32_bf16 v[6:9], v[202:205], v[110:113], v[6:9]
	ds_read_b128 v[110:113], v193 offset:31424
	ds_read_b128 v[202:205], v192 offset:48832
	s_waitcnt lgkmcnt(2)
	v_mfma_f32_16x16x32_bf16 v[2:5], v[114:117], v[198:201], v[2:5]
	ds_read_b128 v[114:117], v159 offset:128
	ds_read_b128 v[206:209], v159 offset:192
	v_lshl_add_u32 v159, v189, 2, s87
	s_waitcnt lgkmcnt(2)
	v_mfma_f32_16x16x32_bf16 v[2:5], v[110:113], v[202:205], v[2:5]
	ds_read_b128 v[110:113], v159 offset:512
	s_waitcnt lgkmcnt(2)
	v_mfma_f32_16x16x32_bf16 v[6:9], v[114:117], v[198:201], v[6:9]
	s_nop 4
	v_sub_f32_e32 v5, v101, v5
	v_sub_f32_e32 v4, v100, v4
	v_sub_f32_e32 v3, v99, v3
	v_sub_f32_e32 v2, v98, v2
	v_cvt_pk_bf16_f32 v114, v2, v3
	s_waitcnt lgkmcnt(0)
	v_pk_mul_f32 v[2:3], v[2:3], v[110:111]
	v_cvt_pk_bf16_f32 v115, v4, v5
	v_pk_mul_f32 v[4:5], v[4:5], v[112:113]
	v_cvt_pk_bf16_f32 v2, v2, v3
	v_cvt_pk_bf16_f32 v3, v4, v5
	ds_write2st64_b64 v194, v[114:115], v[2:3] offset0:112 offset1:121
	ds_read_b128 v[110:113], v159
	v_mfma_f32_16x16x32_bf16 v[114:117], v[206:209], v[202:205], v[6:9]
.Lp4n_stg_B:
	s_cmp_lt_u32 s99, 63
	s_cbranch_scc0 .Lp4n_premid_B
	s_bfe_u32 s45, s42, 0x1000c
	s_cmp_eq_u32 s45, 0
	s_cselect_b64 vcc, -1, 0
	v_mov_b32_e32 v2, v169
	v_cndmask_b32_e32 v6, v162, v161, vcc
	v_cndmask_b32_e32 v7, v164, v163, vcc
	v_cndmask_b32_e32 v8, v166, v165, vcc
	v_cndmask_b32_e32 v9, v168, v167, vcc
	s_waitcnt vmcnt(11)
	ds_write_b128 v2, v[58:61]
	s_waitcnt vmcnt(10)
	ds_write_b128 v2, v[62:65] offset:8704
	ds_write_b128 v170, v[50:53]
	ds_write_b128 v170, v[54:57] offset:9216
	s_waitcnt vmcnt(9)
	v_and_b32_e32 v2, v66, v6
	v_and_b32_e32 v3, v67, v7
	v_and_b32_e32 v4, v68, v8
	v_and_b32_e32 v5, v69, v9
	ds_write_b128 v171, v[2:5] offset:17408
	s_waitcnt vmcnt(8)
	v_and_b32_e32 v2, v70, v6
	v_and_b32_e32 v3, v71, v7
	v_and_b32_e32 v4, v72, v8
	v_and_b32_e32 v5, v73, v9
	v_mov_b32_e32 v6, v172
	s_bfe_u32 s45, s42, 0x60016
	s_cmp_lg_u32 s45, 0
	ds_write_b128 v6, v[2:5]
	s_cbranch_scc1 .Lp4n_cwkeep_B
	s_waitcnt vmcnt(4)
	v_mov_b64_e32 v[84:85], v[24:25]
	v_mov_b64_e32 v[88:89], v[20:21]
	v_mov_b64_e32 v[92:93], v[16:17]
	v_mov_b64_e32 v[96:97], v[12:13]
	v_mov_b64_e32 v[82:83], v[22:23]
	v_mov_b64_e32 v[86:87], v[18:19]
	v_mov_b64_e32 v[90:91], v[14:15]
	v_mov_b64_e32 v[94:95], v[10:11]
.Lp4n_cwkeep_B:
	v_lshlrev_b32_e32 v2, 16, v134
	v_and_b32_e32 v3, 0xffff0000, v134
	v_pk_mul_f32 v[2:3], v[94:95], v[2:3]
	v_lshlrev_b32_e32 v4, 16, v135
	v_and_b32_e32 v5, 0xffff0000, v135
	v_pk_mul_f32 v[4:5], v[96:97], v[4:5]
	v_lshlrev_b32_e32 v6, 16, v138
	v_and_b32_e32 v7, 0xffff0000, v138
	v_pk_fma_f32 v[2:3], v[90:91], v[6:7], v[2:3]
	v_lshlrev_b32_e32 v8, 16, v139
	v_and_b32_e32 v9, 0xffff0000, v139
	v_pk_fma_f32 v[4:5], v[92:93], v[8:9], v[4:5]
	v_lshlrev_b32_e32 v6, 16, v140
	v_and_b32_e32 v7, 0xffff0000, v140
	v_pk_fma_f32 v[2:3], v[86:87], v[6:7], v[2:3]
	v_lshlrev_b32_e32 v8, 16, v141
	v_and_b32_e32 v9, 0xffff0000, v141
	v_pk_fma_f32 v[4:5], v[88:89], v[8:9], v[4:5]
	v_lshlrev_b32_e32 v6, 16, v142
	v_and_b32_e32 v7, 0xffff0000, v142
	v_pk_fma_f32 v[2:3], v[82:83], v[6:7], v[2:3]
	v_lshlrev_b32_e32 v8, 16, v143
	v_and_b32_e32 v9, 0xffff0000, v143
	v_pk_fma_f32 v[4:5], v[84:85], v[8:9], v[4:5]
	v_pk_mul_f32 v[6:7], v[2:3], s[100:101] op_sel_hi:[1,0]
	v_pk_mul_f32 v[8:9], v[4:5], s[100:101] op_sel_hi:[1,0]
	v_exp_f32_e32 v6, v6
	v_exp_f32_e32 v7, v7
	v_exp_f32_e32 v8, v8
	v_exp_f32_e32 v9, v9
	v_pk_add_f32 v[6:7], v[6:7], 1.0 op_sel_hi:[1,0]
	v_pk_add_f32 v[8:9], v[8:9], 1.0 op_sel_hi:[1,0]
	v_rcp_f32_e32 v6, v6
	v_rcp_f32_e32 v7, v7
	v_rcp_f32_e32 v8, v8
	v_rcp_f32_e32 v9, v9
	v_pk_mul_f32 v[2:3], v[2:3], v[6:7]
	v_pk_mul_f32 v[4:5], v[4:5], v[8:9]
	s_waitcnt vmcnt(7)
	v_mul_f32_e32 v2, v181, v2
	v_mul_f32_e32 v3, v181, v3
	v_mul_f32_e32 v4, v181, v4
	v_mul_f32_e32 v5, v181, v5
	v_cvt_pk_bf16_f32 v2, v2, s0
	v_cvt_pk_bf16_f32 v3, v3, s0
	v_cvt_pk_bf16_f32 v4, v4, s0
	v_cvt_pk_bf16_f32 v5, v5, s0
	v_add_u32_e32 v6, v173, v182
	ds_write_b16 v6, v2 offset:26624
	ds_write_b16 v6, v3 offset:26768
	ds_write_b16 v6, v4 offset:26912
	ds_write_b16 v6, v5 offset:27056
	s_and_saveexec_b64 s[8:9], s[4:5]
	s_cbranch_execz .Lp4n_w0done_B
	s_mov_b32 s14, 0x1d400
	s_and_b64 s[20:21], vcc, exec
	s_cselect_b32 s20, 63, 0
	v_and_or_b32 v2, v195, 64, s20
	v_lshlrev_b32_e32 v2, 2, v2
	ds_bpermute_b32 v2, v2, v184
	v_mul_f32_e32 v3, 0x3fb8aa3b, v184
	v_exp_f32_e32 v3, v3
	v_lshl_add_u32 v5, v0, 2, s14
	s_waitcnt lgkmcnt(0)
	v_sub_f32_e32 v4, v2, v184
	v_mul_f32_e32 v4, 0x3fb8aa3b, v4
	v_exp_f32_e32 v4, v4
	v_mul_f32_e32 v6, v185, v3
	ds_write2st64_b32 v5, v3, v6 offset1:1
	ds_write_b32 v5, v4 offset:512
	s_and_b64 exec, exec, s[6:7]
	s_cbranch_execz .Lp4n_w0done_B
	v_mul_f32_e32 v2, 0x3fb8aa3b, v2
	v_exp_f32_e32 v2, v2
	v_mov_b32_e32 v3, s14
	ds_write_b32 v3, v2 offset:768

.Lp4n_premid_B:
.Lp4n_mid_B:
	s_waitcnt lgkmcnt(0)
	s_barrier
	v_mov_b32_e32 v2, s87
	ds_read_b32 v198, v2 offset:768
	ds_read_b128 v[2:5], v196 offset:61952
	ds_read_b128 v[6:9], v196 offset:64256
	v_add_u32_e32 v159, 0x2400, v191
	s_waitcnt lgkmcnt(2)
	v_pk_mul_f32 v[104:105], v[104:105], v[198:199] op_sel_hi:[1,0]
	v_pk_mul_f32 v[102:103], v[102:103], v[198:199] op_sel_hi:[1,0]
	v_pk_mul_f32 v[108:109], v[108:109], v[198:199] op_sel_hi:[1,0]
	v_pk_mul_f32 v[106:107], v[106:107], v[198:199] op_sel_hi:[1,0]
	s_waitcnt lgkmcnt(1)
	v_mfma_f32_16x16x32_bf16 v[102:105], v[74:77], v[2:5], v[102:105]
	ds_read_b128 v[2:5], v196 offset:62016
	s_waitcnt lgkmcnt(1)
	v_mfma_f32_16x16x32_bf16 v[106:109], v[74:77], v[6:9], v[106:109]
	v_readlane_b32 s8, v227, s99
	s_mov_b32 s9, 0
	s_waitcnt lgkmcnt(0)
	v_mfma_f32_16x16x32_bf16 v[2:5], v[78:81], v[2:5], v[102:105]
	s_nop 2
	ds_read_b128 v[102:105], v196 offset:64320
	ds_read_b128 v[198:201], v159
	ds_read_b128 v[202:205], v187 offset:57344
	s_waitcnt lgkmcnt(2)
	v_mfma_f32_16x16x32_bf16 v[6:9], v[78:81], v[102:105], v[106:109]
	v_mul_f32_e64 v104, v116, v112
	v_mul_f32_e64 v105, v117, v113
	v_pk_mul_f32 v[102:103], v[114:115], v[110:111]
	ds_read_b128 v[110:113], v159 offset:64
	ds_read_b128 v[106:109], v187 offset:57408
	s_waitcnt lgkmcnt(2)
	v_mfma_f32_16x16x32_bf16 v[102:105], v[198:201], v[202:205], v[102:105]
	s_bfe_u32 s45, s41, 0x10015
	s_cmp_eq_u32 s45, 0
	s_waitcnt lgkmcnt(0)
	v_mfma_f32_16x16x32_bf16 v[102:105], v[110:113], v[106:109], v[102:105]
	v_lshl_add_u64 v[106:107], s[8:9], 1, v[156:157]
	s_movk_i32 s8, 0x6000
	s_nop 5
	v_cvt_pk_bf16_f32 v102, v102, s0
	global_store_short v[106:107], v102, off
	v_add_co_u32_e32 v102, vcc, s50, v106
	v_cvt_pk_bf16_f32 v108, v103, s0
	s_nop 0
	v_addc_co_u32_e32 v103, vcc, 0, v107, vcc
	global_store_short v[102:103], v108, off
	v_add_co_u32_e32 v102, vcc, s8, v106
	v_cvt_pk_bf16_f32 v104, v104, s0
	s_nop 0
	v_addc_co_u32_e32 v103, vcc, 0, v107, vcc
	global_store_short v[102:103], v104, off
	v_add_co_u32_e32 v102, vcc, 0x9000, v106
	v_cvt_pk_bf16_f32 v104, v105, s0
	s_nop 0
	v_addc_co_u32_e32 v103, vcc, 0, v107, vcc
	global_store_short v[102:103], v104, off
	s_cbranch_scc1 .Lp4n_sjoin_B
	s_bfe_u32 s45, s41, 0x10014
	s_cmp_lg_u32 s45, 0
	s_cbranch_scc1 .Lp4n_nosst_B
	s_bfe_u32 s8, s41, 0x5000f
	s_lshl_b32 s8, s8, 4
	s_bfe_u32 s9, s41, 0x1000c
	s_lshl_b32 s9, s9, 3
	s_bfe_u32 s14, s41, 0x30009
	s_add_i32 s8, s14, s8
	s_bfe_u32 s14, s41, 0x2000d
	s_lshl_b32 s14, s14, 5
	s_add_i32 s8, s8, s9
	s_ashr_i32 s9, s8, 31
	s_lshl_b64 s[8:9], s[8:9], 16
	s_add_u32 s20, s72, s8
	s_addc_u32 s21, s73, s9
	s_lshl_b64 s[8:9], s[14:15], 2
	s_add_u32 s8, s20, s8
	s_addc_u32 s9, s21, s9
	v_lshl_add_u64 v[102:103], s[8:9], 0, v[126:127]
	v_lshl_add_u64 v[102:103], v[102:103], 0, s[18:19]
	v_lshl_add_u64 v[104:105], v[102:103], 0, v[144:145]
	v_lshl_add_u64 v[106:107], v[102:103], 0, v[146:147]
	v_lshl_add_u64 v[108:109], v[102:103], 0, v[148:149]
	v_lshl_add_u64 v[102:103], v[102:103], 0, v[150:151]
	global_store_dword v[104:105], v2, off
	global_store_dword v[106:107], v3, off
	global_store_dword v[108:109], v4, off
	global_store_dword v[102:103], v5, off
	global_store_dword v[104:105], v6, off offset:64
	global_store_dword v[106:107], v7, off offset:64
	global_store_dword v[108:109], v8, off offset:64
	global_store_dword v[102:103], v9, off offset:64

.Lp4n_sjoin_B:
	s_nop 0
	v_cvt_pk_bf16_f32 v102, v2, v3
	v_cvt_pk_bf16_f32 v103, v4, v5
	ds_write_b64 v183, v[102:103] offset:48640
	v_cvt_pk_bf16_f32 v102, v6, v7
	v_cvt_pk_bf16_f32 v103, v8, v9
	s_andn2_b64 vcc, exec, s[10:11]
	ds_write_b64 v183, v[102:103] offset:52992
	s_cbranch_vccnz .Lp4n_end_B
	ds_read_b128 v[74:77], v179
	v_add_u32_e32 v159, 0x1d500, v180
	ds_read_b128 v[102:105], v159
	ds_read_b128 v[106:109], v159 offset:16
	ds_read_b128 v[78:81], v179 offset:64
	s_waitcnt lgkmcnt(3)
	v_lshlrev_b32_e32 v98, 16, v74
	v_and_b32_e32 v99, 0xffff0000, v74
	s_waitcnt lgkmcnt(2)
	v_pk_mul_f32 v[102:103], v[102:103], v[98:99]
	v_lshlrev_b32_e32 v98, 16, v75
	v_and_b32_e32 v99, 0xffff0000, v75
	v_pk_mul_f32 v[104:105], v[104:105], v[98:99]
	v_cvt_pk_bf16_f32 v102, v102, v103
	v_cvt_pk_bf16_f32 v103, v104, v105
	v_lshlrev_b32_e32 v104, 16, v76
	v_and_b32_e32 v105, 0xffff0000, v76
	s_waitcnt lgkmcnt(1)
	v_pk_mul_f32 v[104:105], v[106:107], v[104:105]
	v_lshlrev_b32_e32 v106, 16, v77
	v_and_b32_e32 v107, 0xffff0000, v77
	v_pk_mul_f32 v[106:107], v[108:109], v[106:107]
	v_cvt_pk_bf16_f32 v104, v104, v105
	v_cvt_pk_bf16_f32 v105, v106, v107
	ds_read_b128 v[106:109], v196 offset:17408
	ds_read_b128 v[98:101], v196 offset:17472
	ds_read_b128 v[110:113], v196 offset:19712
	ds_read_b128 v[114:117], v196 offset:19776
	ds_read_b128 v[198:201], v196 offset:22016
	ds_read_b128 v[202:205], v196 offset:22080
	ds_read_b128 v[206:209], v196 offset:24320
	ds_read_b128 v[210:213], v159 offset:128
	ds_read_b128 v[214:217], v196 offset:24384
	s_waitcnt lgkmcnt(8)
	v_mfma_f32_16x16x32_bf16 v[106:109], v[102:105], v[106:109], 0
	v_lshlrev_b32_e32 v218, 16, v78
	v_and_b32_e32 v219, 0xffff0000, v78
	s_waitcnt lgkmcnt(1)
	v_pk_mul_f32 v[210:211], v[210:211], v[218:219]
	v_mfma_f32_16x16x32_bf16 v[110:113], v[102:105], v[110:113], 0
	v_lshlrev_b32_e32 v218, 16, v79
	v_and_b32_e32 v219, 0xffff0000, v79
	v_pk_mul_f32 v[212:213], v[212:213], v[218:219]
	v_mfma_f32_16x16x32_bf16 v[198:201], v[102:105], v[198:201], 0
	v_cvt_pk_bf16_f32 v210, v210, v211
	v_cvt_pk_bf16_f32 v211, v212, v213
	v_lshlrev_b32_e32 v212, 16, v80
	v_mfma_f32_16x16x32_bf16 v[102:105], v[102:105], v[206:209], 0
	ds_read_b128 v[206:209], v159 offset:144
	v_and_b32_e32 v213, 0xffff0000, v80
	s_waitcnt lgkmcnt(0)
	v_pk_mul_f32 v[206:207], v[206:207], v[212:213]
	s_nop 0
	v_cvt_pk_bf16_f32 v212, v206, v207
	v_lshlrev_b32_e32 v206, 16, v81
	v_and_b32_e32 v207, 0xffff0000, v81
	v_pk_mul_f32 v[206:207], v[208:209], v[206:207]
	s_nop 0
	v_cvt_pk_bf16_f32 v213, v206, v207
	s_nop 1
	v_mfma_f32_16x16x32_bf16 v[106:109], v[210:213], v[98:101], v[106:109]
	v_mfma_f32_16x16x32_bf16 v[98:101], v[210:213], v[114:117], v[110:113]
	s_nop 6
	v_cvt_pk_bf16_f32 v106, v106, v107
	v_cvt_pk_bf16_f32 v107, v108, v109
	ds_write_b64 v183, v[106:107] offset:31232
	v_mfma_f32_16x16x32_bf16 v[110:113], v[210:213], v[202:205], v[198:201]
	v_add_u32_e32 v108, v174, v188
	v_cvt_pk_bf16_f32 v106, v98, v99
	v_cvt_pk_bf16_f32 v107, v100, v101
	v_mfma_f32_16x16x32_bf16 v[102:105], v[210:213], v[214:217], v[102:105]
	ds_write_b64 v183, v[106:107] offset:35584
	s_nop 2
	v_cvt_pk_bf16_f32 v106, v110, v111
	v_cvt_pk_bf16_f32 v107, v112, v113
	ds_write_b64 v108, v[106:107] offset:31232
	s_nop 0
	v_cvt_pk_bf16_f32 v102, v102, v103
	v_cvt_pk_bf16_f32 v103, v104, v105
	ds_write_b64 v108, v[102:103] offset:35584
	ds_read_b128 v[102:105], v186 offset:17408
	ds_read_b128 v[106:109], v186 offset:17472
	ds_read_b128 v[98:101], v187 offset:26624
	ds_read_b128 v[110:113], v187 offset:26688
	s_waitcnt lgkmcnt(1)
	v_mfma_f32_16x16x32_bf16 v[102:105], v[102:105], v[98:101], 0
	s_waitcnt lgkmcnt(0)
	v_mfma_f32_16x16x32_bf16 v[98:101], v[106:109], v[110:113], v[102:105]
